# v76 + GEMM unit-start accumulator clear with 64 v_mov_b64 instead of 127 v_mov_b32
# baseline (speedup 1.0000x reference)
.LBB0_225:
	s_ashr_i32 s17, s16, 31
	s_lshl_b64 s[18:19], s[16:17], 20
	s_add_u32 s18, s30, s18
	s_addc_u32 s19, s31, s19
	s_and_b64 s[20:21], s[4:5], exec
	s_cselect_b32 s17, s19, s25
	s_cselect_b32 s54, s18, s24
	s_ashr_i32 s15, s14, 31
	s_lshl_b64 s[20:21], s[14:15], 20
	s_add_u32 s20, s34, s20
	s_addc_u32 s21, s35, s21
	s_and_b64 s[28:29], s[4:5], exec
	s_cselect_b32 s15, s21, s27
	s_cselect_b32 s55, s20, s26
	s_add_u32 s24, s24, 0x80080
	s_addc_u32 s25, s25, 0
	s_add_u32 s58, s26, 0x100
	v_mov_b32_e32 v0, 0
	v_mov_b64_e32 v[0:1], 0
	v_mov_b64_e32 v[2:3], 0
	v_mov_b64_e32 v[4:5], 0
	v_mov_b64_e32 v[6:7], 0
	v_mov_b64_e32 v[8:9], 0
	v_mov_b64_e32 v[10:11], 0
	v_mov_b64_e32 v[12:13], 0
	v_mov_b64_e32 v[14:15], 0
	v_mov_b64_e32 v[16:17], 0
	v_mov_b64_e32 v[18:19], 0
	v_mov_b64_e32 v[20:21], 0
	v_mov_b64_e32 v[22:23], 0
	v_mov_b64_e32 v[24:25], 0
	v_mov_b64_e32 v[26:27], 0
	v_mov_b64_e32 v[28:29], 0
	v_mov_b64_e32 v[30:31], 0
	v_mov_b64_e32 v[32:33], 0
	v_mov_b64_e32 v[34:35], 0
	v_mov_b64_e32 v[36:37], 0
	v_mov_b64_e32 v[38:39], 0
	v_mov_b64_e32 v[40:41], 0
	v_mov_b64_e32 v[42:43], 0
	v_mov_b64_e32 v[44:45], 0
	v_mov_b64_e32 v[46:47], 0
	v_mov_b64_e32 v[48:49], 0
	v_mov_b64_e32 v[50:51], 0
	v_mov_b64_e32 v[52:53], 0
	v_mov_b64_e32 v[54:55], 0
	v_mov_b64_e32 v[56:57], 0
	v_mov_b64_e32 v[58:59], 0
	v_mov_b64_e32 v[60:61], 0
	v_mov_b64_e32 v[62:63], 0
	v_mov_b64_e32 v[64:65], 0
	v_mov_b64_e32 v[66:67], 0
	v_mov_b64_e32 v[68:69], 0
	v_mov_b64_e32 v[70:71], 0
	v_mov_b64_e32 v[72:73], 0
	v_mov_b64_e32 v[74:75], 0
	v_mov_b64_e32 v[76:77], 0
	v_mov_b64_e32 v[78:79], 0
	v_mov_b64_e32 v[80:81], 0
	v_mov_b64_e32 v[82:83], 0
	v_mov_b64_e32 v[84:85], 0
	v_mov_b64_e32 v[86:87], 0
	v_mov_b64_e32 v[88:89], 0
	v_mov_b64_e32 v[90:91], 0
	v_mov_b64_e32 v[92:93], 0
	v_mov_b64_e32 v[94:95], 0
	v_mov_b64_e32 v[96:97], 0
	v_mov_b64_e32 v[98:99], 0
	v_mov_b64_e32 v[100:101], 0
	v_mov_b64_e32 v[102:103], 0
	v_mov_b64_e32 v[104:105], 0
	v_mov_b64_e32 v[106:107], 0
	v_mov_b64_e32 v[108:109], 0
	v_mov_b64_e32 v[110:111], 0
	v_mov_b64_e32 v[112:113], 0
	v_mov_b64_e32 v[114:115], 0
	v_mov_b64_e32 v[116:117], 0
	v_mov_b64_e32 v[118:119], 0
	v_mov_b64_e32 v[120:121], 0
	v_mov_b64_e32 v[122:123], 0
	v_mov_b64_e32 v[124:125], 0
	v_mov_b64_e32 v[126:127], 0
	s_addc_u32 s59, s27, 0
	s_mov_b32 s60, -2

.LBB0_588:
	s_ashr_i32 s35, s34, 31
	s_lshl_b64 s[36:37], s[34:35], 20
	s_add_u32 s36, s60, s36
	s_addc_u32 s37, s61, s37
	s_and_b64 s[38:39], s[8:9], exec
	s_cselect_b32 s35, s37, s49
	s_cselect_b32 s41, s36, s48
	s_ashr_i32 s31, s30, 31
	s_lshl_b64 s[38:39], s[30:31], 20
	s_add_u32 s38, s62, s38
	s_addc_u32 s39, s63, s39
	s_and_b64 s[54:55], s[8:9], exec
	s_cselect_b32 s31, s39, s51
	s_cselect_b32 s73, s38, s50
	s_add_u32 s48, s48, 0x80080
	s_addc_u32 s49, s49, 0
	s_add_u32 s74, s50, 0x100
	v_mov_b32_e32 v0, 0
	v_mov_b64_e32 v[0:1], 0
	v_mov_b64_e32 v[2:3], 0
	v_mov_b64_e32 v[4:5], 0
	v_mov_b64_e32 v[6:7], 0
	v_mov_b64_e32 v[8:9], 0
	v_mov_b64_e32 v[10:11], 0
	v_mov_b64_e32 v[12:13], 0
	v_mov_b64_e32 v[14:15], 0
	v_mov_b64_e32 v[16:17], 0
	v_mov_b64_e32 v[18:19], 0
	v_mov_b64_e32 v[20:21], 0
	v_mov_b64_e32 v[22:23], 0
	v_mov_b64_e32 v[24:25], 0
	v_mov_b64_e32 v[26:27], 0
	v_mov_b64_e32 v[28:29], 0
	v_mov_b64_e32 v[30:31], 0
	v_mov_b64_e32 v[32:33], 0
	v_mov_b64_e32 v[34:35], 0
	v_mov_b64_e32 v[36:37], 0
	v_mov_b64_e32 v[38:39], 0
	v_mov_b64_e32 v[40:41], 0
	v_mov_b64_e32 v[42:43], 0
	v_mov_b64_e32 v[44:45], 0
	v_mov_b64_e32 v[46:47], 0
	v_mov_b64_e32 v[48:49], 0
	v_mov_b64_e32 v[50:51], 0
	v_mov_b64_e32 v[52:53], 0
	v_mov_b64_e32 v[54:55], 0
	v_mov_b64_e32 v[56:57], 0
	v_mov_b64_e32 v[58:59], 0
	v_mov_b64_e32 v[60:61], 0
	v_mov_b64_e32 v[62:63], 0
	v_mov_b64_e32 v[64:65], 0
	v_mov_b64_e32 v[66:67], 0
	v_mov_b64_e32 v[68:69], 0
	v_mov_b64_e32 v[70:71], 0
	v_mov_b64_e32 v[72:73], 0
	v_mov_b64_e32 v[74:75], 0
	v_mov_b64_e32 v[76:77], 0
	v_mov_b64_e32 v[78:79], 0
	v_mov_b64_e32 v[80:81], 0
	v_mov_b64_e32 v[82:83], 0
	v_mov_b64_e32 v[84:85], 0
	v_mov_b64_e32 v[86:87], 0
	v_mov_b64_e32 v[88:89], 0
	v_mov_b64_e32 v[90:91], 0
	v_mov_b64_e32 v[92:93], 0
	v_mov_b64_e32 v[94:95], 0
	v_mov_b64_e32 v[96:97], 0
	v_mov_b64_e32 v[98:99], 0
	v_mov_b64_e32 v[100:101], 0
	v_mov_b64_e32 v[102:103], 0
	v_mov_b64_e32 v[104:105], 0
	v_mov_b64_e32 v[106:107], 0
	v_mov_b64_e32 v[108:109], 0
	v_mov_b64_e32 v[110:111], 0
	v_mov_b64_e32 v[112:113], 0
	v_mov_b64_e32 v[114:115], 0
	v_mov_b64_e32 v[116:117], 0
	v_mov_b64_e32 v[118:119], 0
	v_mov_b64_e32 v[120:121], 0
	v_mov_b64_e32 v[122:123], 0
	v_mov_b64_e32 v[124:125], 0
	v_mov_b64_e32 v[126:127], 0
	s_addc_u32 s75, s51, 0
	s_mov_b32 s77, -2
	s_waitcnt lgkmcnt(0)

.LBB0_672:
	s_ashr_i32 s25, s24, 31
	s_lshl_b64 s[26:27], s[24:25], 20
	s_add_u32 s26, s38, s26
	s_addc_u32 s27, s39, s27
	s_and_b64 s[28:29], s[6:7], exec
	s_cselect_b32 s25, s27, s31
	s_cselect_b32 s65, s26, s30
	s_ashr_i32 s23, s22, 31
	s_lshl_b64 s[28:29], s[22:23], 20
	s_add_u32 s28, s40, s28
	s_addc_u32 s29, s41, s29
	s_and_b64 s[36:37], s[6:7], exec
	s_cselect_b32 s23, s29, s35
	s_cselect_b32 s66, s28, s34
	s_add_u32 s30, s30, 0x80080
	s_addc_u32 s31, s31, 0
	s_add_u32 s67, s34, 0x100
	v_mov_b32_e32 v8, 0
	v_mov_b64_e32 v[0:1], 0
	v_mov_b64_e32 v[2:3], 0
	v_mov_b64_e32 v[4:5], 0
	v_mov_b64_e32 v[6:7], 0
	v_mov_b64_e32 v[8:9], 0
	v_mov_b64_e32 v[10:11], 0
	v_mov_b64_e32 v[12:13], 0
	v_mov_b64_e32 v[14:15], 0
	v_mov_b64_e32 v[16:17], 0
	v_mov_b64_e32 v[18:19], 0
	v_mov_b64_e32 v[20:21], 0
	v_mov_b64_e32 v[22:23], 0
	v_mov_b64_e32 v[24:25], 0
	v_mov_b64_e32 v[26:27], 0
	v_mov_b64_e32 v[28:29], 0
	v_mov_b64_e32 v[30:31], 0
	v_mov_b64_e32 v[32:33], 0
	v_mov_b64_e32 v[34:35], 0
	v_mov_b64_e32 v[36:37], 0
	v_mov_b64_e32 v[38:39], 0
	v_mov_b64_e32 v[40:41], 0
	v_mov_b64_e32 v[42:43], 0
	v_mov_b64_e32 v[44:45], 0
	v_mov_b64_e32 v[46:47], 0
	v_mov_b64_e32 v[48:49], 0
	v_mov_b64_e32 v[50:51], 0
	v_mov_b64_e32 v[52:53], 0
	v_mov_b64_e32 v[54:55], 0
	v_mov_b64_e32 v[56:57], 0
	v_mov_b64_e32 v[58:59], 0
	v_mov_b64_e32 v[60:61], 0
	v_mov_b64_e32 v[62:63], 0
	v_mov_b64_e32 v[64:65], 0
	v_mov_b64_e32 v[66:67], 0
	v_mov_b64_e32 v[68:69], 0
	v_mov_b64_e32 v[70:71], 0
	v_mov_b64_e32 v[72:73], 0
	v_mov_b64_e32 v[74:75], 0
	v_mov_b64_e32 v[76:77], 0
	v_mov_b64_e32 v[78:79], 0
	v_mov_b64_e32 v[80:81], 0
	v_mov_b64_e32 v[82:83], 0
	v_mov_b64_e32 v[84:85], 0
	v_mov_b64_e32 v[86:87], 0
	v_mov_b64_e32 v[88:89], 0
	v_mov_b64_e32 v[90:91], 0
	v_mov_b64_e32 v[92:93], 0
	v_mov_b64_e32 v[94:95], 0
	v_mov_b64_e32 v[96:97], 0
	v_mov_b64_e32 v[98:99], 0
	v_mov_b64_e32 v[100:101], 0
	v_mov_b64_e32 v[102:103], 0
	v_mov_b64_e32 v[104:105], 0
	v_mov_b64_e32 v[106:107], 0
	v_mov_b64_e32 v[108:109], 0
	v_mov_b64_e32 v[110:111], 0
	v_mov_b64_e32 v[112:113], 0
	v_mov_b64_e32 v[114:115], 0
	v_mov_b64_e32 v[116:117], 0
	v_mov_b64_e32 v[118:119], 0
	v_mov_b64_e32 v[120:121], 0
	v_mov_b64_e32 v[122:123], 0
	v_mov_b64_e32 v[124:125], 0
	v_mov_b64_e32 v[126:127], 0
	s_addc_u32 s68, s35, 0
	s_mov_b32 s69, -2

.LBB0_1186:
	s_add_u32 s66, s30, 0x100
	v_mov_b32_e32 v0, 0
	v_mov_b64_e32 v[0:1], 0
	v_mov_b64_e32 v[2:3], 0
	v_mov_b64_e32 v[4:5], 0
	v_mov_b64_e32 v[6:7], 0
	v_mov_b64_e32 v[8:9], 0
	v_mov_b64_e32 v[10:11], 0
	v_mov_b64_e32 v[12:13], 0
	v_mov_b64_e32 v[14:15], 0
	v_mov_b64_e32 v[16:17], 0
	v_mov_b64_e32 v[18:19], 0
	v_mov_b64_e32 v[20:21], 0
	v_mov_b64_e32 v[22:23], 0
	v_mov_b64_e32 v[24:25], 0
	v_mov_b64_e32 v[26:27], 0
	v_mov_b64_e32 v[28:29], 0
	v_mov_b64_e32 v[30:31], 0
	v_mov_b64_e32 v[32:33], 0
	v_mov_b64_e32 v[34:35], 0
	v_mov_b64_e32 v[36:37], 0
	v_mov_b64_e32 v[38:39], 0
	v_mov_b64_e32 v[40:41], 0
	v_mov_b64_e32 v[42:43], 0
	v_mov_b64_e32 v[44:45], 0
	v_mov_b64_e32 v[46:47], 0
	v_mov_b64_e32 v[48:49], 0
	v_mov_b64_e32 v[50:51], 0
	v_mov_b64_e32 v[52:53], 0
	v_mov_b64_e32 v[54:55], 0
	v_mov_b64_e32 v[56:57], 0
	v_mov_b64_e32 v[58:59], 0
	v_mov_b64_e32 v[60:61], 0
	v_mov_b64_e32 v[62:63], 0
	v_mov_b64_e32 v[64:65], 0
	v_mov_b64_e32 v[66:67], 0
	v_mov_b64_e32 v[68:69], 0
	v_mov_b64_e32 v[70:71], 0
	v_mov_b64_e32 v[72:73], 0
	v_mov_b64_e32 v[74:75], 0
	v_mov_b64_e32 v[76:77], 0
	v_mov_b64_e32 v[78:79], 0
	v_mov_b64_e32 v[80:81], 0
	v_mov_b64_e32 v[82:83], 0
	v_mov_b64_e32 v[84:85], 0
	v_mov_b64_e32 v[86:87], 0
	v_mov_b64_e32 v[88:89], 0
	v_mov_b64_e32 v[90:91], 0
	v_mov_b64_e32 v[92:93], 0
	v_mov_b64_e32 v[94:95], 0
	v_mov_b64_e32 v[96:97], 0
	v_mov_b64_e32 v[98:99], 0
	v_mov_b64_e32 v[100:101], 0
	v_mov_b64_e32 v[102:103], 0
	v_mov_b64_e32 v[104:105], 0
	v_mov_b64_e32 v[106:107], 0
	v_mov_b64_e32 v[108:109], 0
	v_mov_b64_e32 v[110:111], 0
	v_mov_b64_e32 v[112:113], 0
	v_mov_b64_e32 v[114:115], 0
	v_mov_b64_e32 v[116:117], 0
	v_mov_b64_e32 v[118:119], 0
	v_mov_b64_e32 v[120:121], 0
	v_mov_b64_e32 v[122:123], 0
	v_mov_b64_e32 v[124:125], 0
	v_mov_b64_e32 v[126:127], 0
	s_addc_u32 s67, s31, 0
	s_mov_b32 s68, -2
	s_waitcnt lgkmcnt(0)

.LBB0_1270:
	s_ashr_i32 s25, s24, 31
	s_lshl_b64 s[26:27], s[24:25], 20
	s_add_u32 s26, s38, s26
	s_addc_u32 s27, s39, s27
	s_and_b64 s[28:29], s[6:7], exec
	s_cselect_b32 s25, s27, s31
	s_cselect_b32 s63, s26, s30
	s_ashr_i32 s23, s22, 31
	s_lshl_b64 s[28:29], s[22:23], 20
	s_add_u32 s28, s40, s28
	s_addc_u32 s29, s41, s29
	s_and_b64 s[36:37], s[6:7], exec
	s_cselect_b32 s23, s29, s35
	s_cselect_b32 s64, s28, s34
	s_add_u32 s30, s30, 0x80080
	s_addc_u32 s31, s31, 0
	s_add_u32 s65, s34, 0x100
	v_mov_b32_e32 v0, 0
	v_mov_b64_e32 v[0:1], 0
	v_mov_b64_e32 v[2:3], 0
	v_mov_b64_e32 v[4:5], 0
	v_mov_b64_e32 v[6:7], 0
	v_mov_b64_e32 v[8:9], 0
	v_mov_b64_e32 v[10:11], 0
	v_mov_b64_e32 v[12:13], 0
	v_mov_b64_e32 v[14:15], 0
	v_mov_b64_e32 v[16:17], 0
	v_mov_b64_e32 v[18:19], 0
	v_mov_b64_e32 v[20:21], 0
	v_mov_b64_e32 v[22:23], 0
	v_mov_b64_e32 v[24:25], 0
	v_mov_b64_e32 v[26:27], 0
	v_mov_b64_e32 v[28:29], 0
	v_mov_b64_e32 v[30:31], 0
	v_mov_b64_e32 v[32:33], 0
	v_mov_b64_e32 v[34:35], 0
	v_mov_b64_e32 v[36:37], 0
	v_mov_b64_e32 v[38:39], 0
	v_mov_b64_e32 v[40:41], 0
	v_mov_b64_e32 v[42:43], 0
	v_mov_b64_e32 v[44:45], 0
	v_mov_b64_e32 v[46:47], 0
	v_mov_b64_e32 v[48:49], 0
	v_mov_b64_e32 v[50:51], 0
	v_mov_b64_e32 v[52:53], 0
	v_mov_b64_e32 v[54:55], 0
	v_mov_b64_e32 v[56:57], 0
	v_mov_b64_e32 v[58:59], 0
	v_mov_b64_e32 v[60:61], 0
	v_mov_b64_e32 v[62:63], 0
	v_mov_b64_e32 v[64:65], 0
	v_mov_b64_e32 v[66:67], 0
	v_mov_b64_e32 v[68:69], 0
	v_mov_b64_e32 v[70:71], 0
	v_mov_b64_e32 v[72:73], 0
	v_mov_b64_e32 v[74:75], 0
	v_mov_b64_e32 v[76:77], 0
	v_mov_b64_e32 v[78:79], 0
	v_mov_b64_e32 v[80:81], 0
	v_mov_b64_e32 v[82:83], 0
	v_mov_b64_e32 v[84:85], 0
	v_mov_b64_e32 v[86:87], 0
	v_mov_b64_e32 v[88:89], 0
	v_mov_b64_e32 v[90:91], 0
	v_mov_b64_e32 v[92:93], 0
	v_mov_b64_e32 v[94:95], 0
	v_mov_b64_e32 v[96:97], 0
	v_mov_b64_e32 v[98:99], 0
	v_mov_b64_e32 v[100:101], 0
	v_mov_b64_e32 v[102:103], 0
	v_mov_b64_e32 v[104:105], 0
	v_mov_b64_e32 v[106:107], 0
	v_mov_b64_e32 v[108:109], 0
	v_mov_b64_e32 v[110:111], 0
	v_mov_b64_e32 v[112:113], 0
	v_mov_b64_e32 v[114:115], 0
	v_mov_b64_e32 v[116:117], 0
	v_mov_b64_e32 v[118:119], 0
	v_mov_b64_e32 v[120:121], 0
	v_mov_b64_e32 v[122:123], 0
	v_mov_b64_e32 v[124:125], 0
	v_mov_b64_e32 v[126:127], 0
	s_addc_u32 s66, s35, 0
	s_mov_b32 s67, -2

.LBB0_1419:
	s_ashr_i32 s27, s26, 31
	s_lshl_b64 s[28:29], s[26:27], 20
	s_add_u32 s28, s48, s28
	s_addc_u32 s29, s49, s29
	s_and_b64 s[30:31], s[8:9], exec
	s_cselect_b32 s27, s29, s39
	s_cselect_b32 s35, s28, s38
	s_ashr_i32 s25, s24, 31
	s_lshl_b64 s[30:31], s[24:25], 20
	s_add_u32 s30, s50, s30
	s_addc_u32 s31, s51, s31
	s_and_b64 s[42:43], s[8:9], exec
	s_cselect_b32 s25, s31, s41
	s_cselect_b32 s65, s30, s40
	s_add_u32 s38, s38, 0x80080
	s_addc_u32 s39, s39, 0
	s_add_u32 s66, s40, 0x100
	v_mov_b32_e32 v0, 0
	v_mov_b64_e32 v[0:1], 0
	v_mov_b64_e32 v[2:3], 0
	v_mov_b64_e32 v[4:5], 0
	v_mov_b64_e32 v[6:7], 0
	v_mov_b64_e32 v[8:9], 0
	v_mov_b64_e32 v[10:11], 0
	v_mov_b64_e32 v[12:13], 0
	v_mov_b64_e32 v[14:15], 0
	v_mov_b64_e32 v[16:17], 0
	v_mov_b64_e32 v[18:19], 0
	v_mov_b64_e32 v[20:21], 0
	v_mov_b64_e32 v[22:23], 0
	v_mov_b64_e32 v[24:25], 0
	v_mov_b64_e32 v[26:27], 0
	v_mov_b64_e32 v[28:29], 0
	v_mov_b64_e32 v[30:31], 0
	v_mov_b64_e32 v[32:33], 0
	v_mov_b64_e32 v[34:35], 0
	v_mov_b64_e32 v[36:37], 0
	v_mov_b64_e32 v[38:39], 0
	v_mov_b64_e32 v[40:41], 0
	v_mov_b64_e32 v[42:43], 0
	v_mov_b64_e32 v[44:45], 0
	v_mov_b64_e32 v[46:47], 0
	v_mov_b64_e32 v[48:49], 0
	v_mov_b64_e32 v[50:51], 0
	v_mov_b64_e32 v[52:53], 0
	v_mov_b64_e32 v[54:55], 0
	v_mov_b64_e32 v[56:57], 0
	v_mov_b64_e32 v[58:59], 0
	v_mov_b64_e32 v[60:61], 0
	v_mov_b64_e32 v[62:63], 0
	v_mov_b64_e32 v[64:65], 0
	v_mov_b64_e32 v[66:67], 0
	v_mov_b64_e32 v[68:69], 0
	v_mov_b64_e32 v[70:71], 0
	v_mov_b64_e32 v[72:73], 0
	v_mov_b64_e32 v[74:75], 0
	v_mov_b64_e32 v[76:77], 0
	v_mov_b64_e32 v[78:79], 0
	v_mov_b64_e32 v[80:81], 0
	v_mov_b64_e32 v[82:83], 0
	v_mov_b64_e32 v[84:85], 0
	v_mov_b64_e32 v[86:87], 0
	v_mov_b64_e32 v[88:89], 0
	v_mov_b64_e32 v[90:91], 0
	v_mov_b64_e32 v[92:93], 0
	v_mov_b64_e32 v[94:95], 0
	v_mov_b64_e32 v[96:97], 0
	v_mov_b64_e32 v[98:99], 0
	v_mov_b64_e32 v[100:101], 0
	v_mov_b64_e32 v[102:103], 0
	v_mov_b64_e32 v[104:105], 0
	v_mov_b64_e32 v[106:107], 0
	v_mov_b64_e32 v[108:109], 0
	v_mov_b64_e32 v[110:111], 0
	v_mov_b64_e32 v[112:113], 0
	v_mov_b64_e32 v[114:115], 0
	v_mov_b64_e32 v[116:117], 0
	v_mov_b64_e32 v[118:119], 0
	v_mov_b64_e32 v[120:121], 0
	v_mov_b64_e32 v[122:123], 0
	v_mov_b64_e32 v[124:125], 0
	v_mov_b64_e32 v[126:127], 0
	s_addc_u32 s67, s41, 0
	s_mov_b32 s68, -2
	s_waitcnt lgkmcnt(0)

.LBB0_1503:
	s_ashr_i32 s23, s22, 31
	s_lshl_b64 s[24:25], s[22:23], 20
	s_add_u32 s24, s36, s24
	s_addc_u32 s25, s37, s25
	s_and_b64 s[26:27], s[6:7], exec
	s_cselect_b32 s23, s25, s29
	s_cselect_b32 s61, s24, s28
	s_ashr_i32 s21, s20, 31
	s_lshl_b64 s[26:27], s[20:21], 20
	s_add_u32 s26, s38, s26
	s_addc_u32 s27, s39, s27
	s_and_b64 s[34:35], s[6:7], exec
	s_cselect_b32 s21, s27, s31
	s_cselect_b32 s62, s26, s30
	s_add_u32 s28, s28, 0x80080
	s_addc_u32 s29, s29, 0
	s_add_u32 s63, s30, 0x100
	v_mov_b32_e32 v8, 0
	v_mov_b64_e32 v[0:1], 0
	v_mov_b64_e32 v[2:3], 0
	v_mov_b64_e32 v[4:5], 0
	v_mov_b64_e32 v[6:7], 0
	v_mov_b64_e32 v[8:9], 0
	v_mov_b64_e32 v[10:11], 0
	v_mov_b64_e32 v[12:13], 0
	v_mov_b64_e32 v[14:15], 0
	v_mov_b64_e32 v[16:17], 0
	v_mov_b64_e32 v[18:19], 0
	v_mov_b64_e32 v[20:21], 0
	v_mov_b64_e32 v[22:23], 0
	v_mov_b64_e32 v[24:25], 0
	v_mov_b64_e32 v[26:27], 0
	v_mov_b64_e32 v[28:29], 0
	v_mov_b64_e32 v[30:31], 0
	v_mov_b64_e32 v[32:33], 0
	v_mov_b64_e32 v[34:35], 0
	v_mov_b64_e32 v[36:37], 0
	v_mov_b64_e32 v[38:39], 0
	v_mov_b64_e32 v[40:41], 0
	v_mov_b64_e32 v[42:43], 0
	v_mov_b64_e32 v[44:45], 0
	v_mov_b64_e32 v[46:47], 0
	v_mov_b64_e32 v[48:49], 0
	v_mov_b64_e32 v[50:51], 0
	v_mov_b64_e32 v[52:53], 0
	v_mov_b64_e32 v[54:55], 0
	v_mov_b64_e32 v[56:57], 0
	v_mov_b64_e32 v[58:59], 0
	v_mov_b64_e32 v[60:61], 0
	v_mov_b64_e32 v[62:63], 0
	v_mov_b64_e32 v[64:65], 0
	v_mov_b64_e32 v[66:67], 0
	v_mov_b64_e32 v[68:69], 0
	v_mov_b64_e32 v[70:71], 0
	v_mov_b64_e32 v[72:73], 0
	v_mov_b64_e32 v[74:75], 0
	v_mov_b64_e32 v[76:77], 0
	v_mov_b64_e32 v[78:79], 0
	v_mov_b64_e32 v[80:81], 0
	v_mov_b64_e32 v[82:83], 0
	v_mov_b64_e32 v[84:85], 0
	v_mov_b64_e32 v[86:87], 0
	v_mov_b64_e32 v[88:89], 0
	v_mov_b64_e32 v[90:91], 0
	v_mov_b64_e32 v[92:93], 0
	v_mov_b64_e32 v[94:95], 0
	v_mov_b64_e32 v[96:97], 0
	v_mov_b64_e32 v[98:99], 0
	v_mov_b64_e32 v[100:101], 0
	v_mov_b64_e32 v[102:103], 0
	v_mov_b64_e32 v[104:105], 0
	v_mov_b64_e32 v[106:107], 0
	v_mov_b64_e32 v[108:109], 0
	v_mov_b64_e32 v[110:111], 0
	v_mov_b64_e32 v[112:113], 0
	v_mov_b64_e32 v[114:115], 0
	v_mov_b64_e32 v[116:117], 0
	v_mov_b64_e32 v[118:119], 0
	v_mov_b64_e32 v[120:121], 0
	v_mov_b64_e32 v[122:123], 0
	v_mov_b64_e32 v[124:125], 0
	v_mov_b64_e32 v[126:127], 0
	s_addc_u32 s64, s31, 0
	s_mov_b32 s65, -2

.LBB0_2010:
	s_add_u32 s66, s36, 0x100
	v_mov_b32_e32 v0, 0
	v_mov_b64_e32 v[0:1], 0
	v_mov_b64_e32 v[2:3], 0
	v_mov_b64_e32 v[4:5], 0
	v_mov_b64_e32 v[6:7], 0
	v_mov_b64_e32 v[8:9], 0
	v_mov_b64_e32 v[10:11], 0
	v_mov_b64_e32 v[12:13], 0
	v_mov_b64_e32 v[14:15], 0
	v_mov_b64_e32 v[16:17], 0
	v_mov_b64_e32 v[18:19], 0
	v_mov_b64_e32 v[20:21], 0
	v_mov_b64_e32 v[22:23], 0
	v_mov_b64_e32 v[24:25], 0
	v_mov_b64_e32 v[26:27], 0
	v_mov_b64_e32 v[28:29], 0
	v_mov_b64_e32 v[30:31], 0
	v_mov_b64_e32 v[32:33], 0
	v_mov_b64_e32 v[34:35], 0
	v_mov_b64_e32 v[36:37], 0
	v_mov_b64_e32 v[38:39], 0
	v_mov_b64_e32 v[40:41], 0
	v_mov_b64_e32 v[42:43], 0
	v_mov_b64_e32 v[44:45], 0
	v_mov_b64_e32 v[46:47], 0
	v_mov_b64_e32 v[48:49], 0
	v_mov_b64_e32 v[50:51], 0
	v_mov_b64_e32 v[52:53], 0
	v_mov_b64_e32 v[54:55], 0
	v_mov_b64_e32 v[56:57], 0
	v_mov_b64_e32 v[58:59], 0
	v_mov_b64_e32 v[60:61], 0
	v_mov_b64_e32 v[62:63], 0
	v_mov_b64_e32 v[64:65], 0
	v_mov_b64_e32 v[66:67], 0
	v_mov_b64_e32 v[68:69], 0
	v_mov_b64_e32 v[70:71], 0
	v_mov_b64_e32 v[72:73], 0
	v_mov_b64_e32 v[74:75], 0
	v_mov_b64_e32 v[76:77], 0
	v_mov_b64_e32 v[78:79], 0
	v_mov_b64_e32 v[80:81], 0
	v_mov_b64_e32 v[82:83], 0
	v_mov_b64_e32 v[84:85], 0
	v_mov_b64_e32 v[86:87], 0
	v_mov_b64_e32 v[88:89], 0
	v_mov_b64_e32 v[90:91], 0
	v_mov_b64_e32 v[92:93], 0
	v_mov_b64_e32 v[94:95], 0
	v_mov_b64_e32 v[96:97], 0
	v_mov_b64_e32 v[98:99], 0
	v_mov_b64_e32 v[100:101], 0
	v_mov_b64_e32 v[102:103], 0
	v_mov_b64_e32 v[104:105], 0
	v_mov_b64_e32 v[106:107], 0
	v_mov_b64_e32 v[108:109], 0
	v_mov_b64_e32 v[110:111], 0
	v_mov_b64_e32 v[112:113], 0
	v_mov_b64_e32 v[114:115], 0
	v_mov_b64_e32 v[116:117], 0
	v_mov_b64_e32 v[118:119], 0
	v_mov_b64_e32 v[120:121], 0
	v_mov_b64_e32 v[122:123], 0
	v_mov_b64_e32 v[124:125], 0
	v_mov_b64_e32 v[126:127], 0
	s_addc_u32 s67, s37, 0
	s_mov_b32 s68, -2
	s_waitcnt lgkmcnt(0)
